# c39 + phase-0 adaLN modulation loop: weight-row loads prefetched one 8-row block ahead (landing regs v112-v126, copied to v128-v142), so their HBM latency overlaps the silu math instead of serialising
# speedup vs baseline: 1.0071x; 1.0071x over previous
; __device__ __forceinline__ float siluf(float v) { return v * __builtin_amdgcn_rcpf(1.f + __builtin_amdgcn_exp2f(-1.4426950408889634f * v)); }
; __device__ void phase0(const Params& p, unsigned char* smem) {
;     ...
;             const int it = item - I_T, l = it / 96, col0 = (it % 96) * 32, cl = tid & 31, ks = tid >> 5;
;             float a0 = 0.f, a1 = 0.f, a2 = 0.f, a3 = 0.f;
;             const float* wp = p.w_ada + ((size_t)l * 1024 + ks * 128) * 3072 + col0 + cl;
; #pragma unroll 8
;             for (int k = 0; k < 128; ++k) {
;                 const float wv = wp[(size_t)k * 3072]; const int kk = ks * 128 + k;
;                 a0 += siluf(p.c[kk]) * wv; a1 += siluf(p.c[1024 + kk]) * wv; a2 += siluf(p.c[2048 + kk]) * wv; a3 += siluf(p.c[3072 + kk]) * wv;
.LBB0_144:
	s_cmpk_lt_i32 s16, 0x1580
	s_cbranch_scc1 .LBB0_143
	s_cmpk_lg_i32 s16, 0x1640
	s_mov_b64 s[6:7], -1
	s_cbranch_scc0 .LBB0_151
	s_add_i32 s6, s16, 0xffffea80
	s_add_i32 s7, s16, 0xffffea20
	s_cmpk_lt_u32 s6, 0x60
	s_cselect_b32 s40, s6, s7
	s_cmpk_gt_u32 s6, 0x5f
	s_cselect_b64 s[12:13], -1, 0
	s_and_b64 s[6:7], s[12:13], exec
	s_cselect_b32 s6, 0x400, 0
	v_or_b32_e32 v4, s6, v18
	s_lshl_b64 s[6:7], s[40:41], 7
	v_mov_b64_e32 v[2:3], s[6:7]
	v_mad_u64_u32 v[2:3], s[6:7], v4, s18, v[2:3]
	v_lshl_add_u64 v[38:39], v[26:27], 0, v[2:3]
	s_mov_b64 s[98:99], 0x3000
	s_mov_b32 s100, 0xffff4000
	s_mov_b32 s101, -1
	v_lshl_add_u64 v[144:145], v[38:39], 0, s[100:101]
	global_load_dword v112, v[144:145], off
	v_lshl_add_u64 v[144:145], v[144:145], 0, s[98:99]
	global_load_dword v114, v[144:145], off
	v_lshl_add_u64 v[144:145], v[144:145], 0, s[98:99]
	global_load_dword v116, v[144:145], off
	v_lshl_add_u64 v[144:145], v[144:145], 0, s[98:99]
	global_load_dword v118, v[144:145], off
	v_lshl_add_u64 v[144:145], v[144:145], 0, s[98:99]
	global_load_dword v120, v[144:145], off
	v_lshl_add_u64 v[144:145], v[144:145], 0, s[98:99]
	global_load_dword v122, v[144:145], off
	v_lshl_add_u64 v[144:145], v[144:145], 0, s[98:99]
	global_load_dword v124, v[144:145], off
	v_lshl_add_u64 v[144:145], v[144:145], 0, s[98:99]
	global_load_dword v126, v[144:145], off
	v_mov_b32_e32 v2, 0
	s_mov_b64 s[14:15], 0
	v_mov_b32_e32 v3, v2
	v_mov_b32_e32 v4, v2
	v_mov_b32_e32 v5, v2
.LBB0_147:
	v_add_co_u32_e32 v74, vcc, 0xffff4000, v38
	s_mov_b32 s10, 0xffff7000
	s_mov_b64 s[6:7], vcc
	v_add_co_u32_e32 v76, vcc, s10, v38
	s_movk_i32 s10, 0xa000
	s_nop 0
	v_addc_co_u32_e32 v77, vcc, -1, v39, vcc
	v_lshl_add_u64 v[10:11], v[24:25], 0, s[14:15]
	v_add_co_u32_e32 v78, vcc, s10, v38
	s_mov_b64 s[10:11], 0x1000
	s_nop 0
	v_addc_co_u32_e32 v79, vcc, -1, v39, vcc
	v_lshl_add_u64 v[12:13], v[10:11], 0, s[10:11]
	s_movk_i32 s10, 0x2000
	v_add_co_u32_e32 v40, vcc, s10, v10
	s_mov_b64 s[10:11], 0x2000
	global_load_dwordx4 v[48:51], v[10:11], off
	global_load_dwordx4 v[52:55], v[10:11], off offset:16
	v_lshl_add_u64 v[14:15], v[10:11], 0, s[10:11]
	s_mov_b64 s[10:11], 0x3000
	v_lshl_add_u64 v[16:17], v[10:11], 0, s[10:11]
	v_add_co_u32_e64 v6, s[10:11], s18, v10
	v_addc_co_u32_e32 v41, vcc, 0, v11, vcc
	s_nop 0
	v_addc_co_u32_e64 v7, s[10:11], 0, v11, s[10:11]
	global_load_dwordx4 v[6:9], v[6:7], off
	s_nop 0
	global_load_dwordx4 v[56:59], v[12:13], off offset:16
	global_load_dwordx4 v[60:63], v[14:15], off offset:16
	s_nop 0
	global_load_dwordx4 v[14:17], v[16:17], off offset:16
	s_nop 0
	global_load_dwordx4 v[10:13], v[40:41], off offset:-4096
	global_load_dwordx4 v[64:67], v[40:41], off
	s_movk_i32 s10, 0xd000
	s_add_u32 s14, s14, 32
	s_addc_u32 s15, s15, 0
	s_cmpk_eq_i32 s14, 0x200
	s_mov_b32 s100, 0xc000
	s_mov_b32 s101, 0
	s_cmov_b32 s100, 0xffff4000
	s_cmov_b32 s101, -1
	s_waitcnt vmcnt(8)
	v_mov_b32_e32 v128, v112
	v_mov_b32_e32 v130, v114
	v_mov_b32_e32 v132, v116
	v_mov_b32_e32 v134, v118
	v_mov_b32_e32 v136, v120
	v_mov_b32_e32 v138, v122
	v_mov_b32_e32 v140, v124
	v_mov_b32_e32 v142, v126
	v_lshl_add_u64 v[144:145], v[38:39], 0, s[100:101]
	global_load_dword v112, v[144:145], off
	v_lshl_add_u64 v[144:145], v[144:145], 0, s[98:99]
	global_load_dword v114, v[144:145], off
	v_lshl_add_u64 v[144:145], v[144:145], 0, s[98:99]
	global_load_dword v116, v[144:145], off
	v_lshl_add_u64 v[144:145], v[144:145], 0, s[98:99]
	global_load_dword v118, v[144:145], off
	v_lshl_add_u64 v[144:145], v[144:145], 0, s[98:99]
	global_load_dword v120, v[144:145], off
	v_lshl_add_u64 v[144:145], v[144:145], 0, s[98:99]
	global_load_dword v122, v[144:145], off
	v_lshl_add_u64 v[144:145], v[144:145], 0, s[98:99]
	global_load_dword v124, v[144:145], off
	v_lshl_add_u64 v[144:145], v[144:145], 0, s[98:99]
	global_load_dword v126, v[144:145], off
	s_waitcnt vmcnt(15)
	v_mul_f32_e32 v20, 0xbfb8aa3b, v48
	v_mov_b32_e32 v42, v48
	v_mul_f32_e32 v44, 0xbfb8aa3b, v51
	s_waitcnt vmcnt(14)
	v_mul_f32_e32 v48, 0xbfb8aa3b, v53
	v_exp_f32_e32 v71, v44
	v_mul_f32_e32 v43, 0xbfb8aa3b, v50
	v_mov_b32_e32 v40, v50
	v_mul_f32_e32 v46, 0xbfb8aa3b, v52
	s_waitcnt vmcnt(13)
	v_mul_f32_e32 v70, 0xbfb8aa3b, v8
	v_mov_b32_e32 v47, v8
	v_exp_f32_e32 v8, v48
	s_waitcnt vmcnt(12)
	v_mul_f32_e32 v44, 0xbfb8aa3b, v57
	v_mov_b32_e32 v72, v52
	v_mul_f32_e32 v50, 0xbfb8aa3b, v54
	v_mul_f32_e32 v52, 0xbfb8aa3b, v55
	v_mul_f32_e32 v48, 0xbfb8aa3b, v59
	v_exp_f32_e32 v44, v44
	v_exp_f32_e32 v86, v46
	v_exp_f32_e32 v94, v50
	v_exp_f32_e32 v46, v52
	v_exp_f32_e32 v50, v48
	v_add_f32_e32 v8, 1.0, v8
	v_rcp_f32_e32 v48, v8
	v_add_f32_e32 v8, 1.0, v44
	v_mul_f32_e32 v41, 0xbfb8aa3b, v49
	v_exp_f32_e32 v69, v43
	s_waitcnt vmcnt(11)
	v_mul_f32_e32 v88, 0xbfb8aa3b, v60
	s_waitcnt vmcnt(10)
	v_mul_f32_e32 v89, 0xbfb8aa3b, v14
	v_mov_b32_e32 v82, v60
	v_mov_b32_e32 v83, v14
	v_mul_f32_e32 v60, 0xbfb8aa3b, v58
	v_mov_b32_e32 v81, v58
	v_mov_b32_e32 v58, v55
	v_mul_f32_e32 v55, 0xbfb8aa3b, v61
	v_mov_b32_e32 v14, v61
	s_waitcnt vmcnt(9)
	v_mul_f32_e32 v61, 0xbfb8aa3b, v10
	v_mov_b32_e32 v43, v10
	v_mov_b32_e32 v10, v49
	v_add_f32_e32 v46, 1.0, v46
	v_rcp_f32_e32 v49, v8
	v_add_f32_e32 v8, 1.0, v50
	v_mul_f32_e32 v87, 0xbfb8aa3b, v56
	v_mov_b32_e32 v73, v56
	v_mov_b32_e32 v56, v53
	v_rcp_f32_e32 v52, v46
	v_rcp_f32_e32 v53, v8
	v_mov_b32_e32 v80, v54
	v_exp_f32_e32 v20, v20
	v_mul_f32_e32 v54, 0xbfb8aa3b, v6
	v_exp_f32_e32 v68, v41
	v_mul_f32_e32 v90, 0xbfb8aa3b, v12
	v_mov_b32_e32 v41, v12
	v_mov_b32_e32 v12, v51
	v_pk_mul_f32 v[50:51], v[56:57], v[48:49]
	v_pk_mul_f32 v[48:49], v[58:59], v[52:53]
	v_exp_f32_e32 v53, v54
	s_waitcnt vmcnt(8)
; __device__ __forceinline__ float siluf(float v) { return v * __builtin_amdgcn_rcpf(1.f + __builtin_amdgcn_exp2f(-1.4426950408889634f * v)); }
; __device__ void phase0(const Params& p, unsigned char* smem) {
;     ...
;             for (int k = 0; k < 128; ++k) {
;                 const float wv = wp[(size_t)k * 3072]; const int kk = ks * 128 + k;
;                 a0 += siluf(p.c[kk]) * wv; a1 += siluf(p.c[1024 + kk]) * wv; a2 += siluf(p.c[2048 + kk]) * wv; a3 += siluf(p.c[3072 + kk]) * wv;
;             }
;             float* red = (float*)smem;
;             red[(ks * 32 + cl) * 4 + 0] = a0; red[(ks * 32 + cl) * 4 + 1] = a1; red[(ks * 32 + cl) * 4 + 2] = a2; red[(ks * 32 + cl) * 4 + 3] = a3;
;             __syncthreads();
;             if (tid < 128) { const int b = tid >> 5, c2 = tid & 31; float s = 0.f;
; #pragma unroll
;                 for (int k = 0; k < 8; ++k) s += red[(k * 32 + c2) * 4 + b];
;                 ((float*)(p.ws + WS_MOD))[(l * 4 + b) * 3072 + col0 + c2] = s + p.b_ada[l * 3072 + col0 + c2]; }
	v_mul_f32_e32 v58, 0xbfb8aa3b, v66
	v_mov_b32_e32 v46, v66
	v_exp_f32_e32 v66, v87
	v_mul_f32_e32 v75, 0xbfb8aa3b, v9
	v_mov_b32_e32 v45, v6
	v_mul_f32_e32 v6, 0xbfb8aa3b, v7
	v_mul_f32_e32 v91, 0xbfb8aa3b, v62
	v_mul_f32_e32 v92, 0xbfb8aa3b, v16
	v_mov_b32_e32 v84, v62
	v_mul_f32_e32 v62, 0xbfb8aa3b, v63
	v_mul_f32_e32 v95, 0xbfb8aa3b, v17
	v_mul_f32_e32 v52, 0xbfb8aa3b, v64
	v_mov_b32_e32 v44, v64
	v_exp_f32_e32 v64, v70
	v_exp_f32_e32 v70, v75
	v_exp_f32_e32 v75, v89
	v_mul_f32_e32 v54, 0xbfb8aa3b, v11
	v_exp_f32_e32 v57, v6
	v_mov_b32_e32 v8, v67
	v_mul_f32_e32 v59, 0xbfb8aa3b, v67
	v_exp_f32_e32 v67, v88
	v_exp_f32_e32 v60, v60
	v_exp_f32_e32 v88, v92
	v_exp_f32_e32 v62, v62
	v_exp_f32_e32 v89, v95
	v_exp_f32_e32 v92, v52
	v_add_f32_e32 v20, 1.0, v20
	v_exp_f32_e32 v95, v54
	v_add_f32_e32 v54, 1.0, v86
	v_rcp_f32_e32 v52, v20
	v_add_f32_e32 v20, 1.0, v53
	v_add_f32_e32 v53, 1.0, v66
	v_mul_f32_e32 v56, 0xbfb8aa3b, v65
	v_exp_f32_e32 v87, v91
	v_rcp_f32_e32 v106, v54
	v_rcp_f32_e32 v107, v53
	v_mov_b32_e32 v85, v16
	v_mov_b32_e32 v16, v63
	v_mul_f32_e32 v63, 0xbfb8aa3b, v15
	v_exp_f32_e32 v61, v61
	v_exp_f32_e32 v105, v56
	v_exp_f32_e32 v110, v59
	v_add_f32_e32 v59, 1.0, v75
	v_exp_f32_e32 v55, v55
	v_exp_f32_e32 v63, v63
	v_exp_f32_e32 v108, v90
	v_exp_f32_e32 v109, v58
	v_add_f32_e32 v58, 1.0, v94
	v_rcp_f32_e32 v91, v59
	v_add_f32_e32 v53, 1.0, v60
	v_add_f32_e32 v59, 1.0, v88
	v_add_f32_e32 v60, 1.0, v62
	v_add_f32_e32 v62, 1.0, v89
	v_add_f32_e32 v66, 1.0, v57
	v_add_f32_e32 v57, 1.0, v92
	v_add_co_u32_e32 v94, vcc, s10, v38
	v_mov_b32_e32 v6, v65
	v_mul_f32_e32 v65, 0xbfb8aa3b, v13
	v_rcp_f32_e32 v89, v59
	v_rcp_f32_e32 v59, v62
	v_rcp_f32_e32 v62, v57
	v_add_f32_e32 v57, 1.0, v95
	v_addc_co_u32_e32 v95, vcc, -1, v39, vcc
	v_exp_f32_e32 v65, v65
	v_add_f32_e32 v54, 1.0, v67
	v_rcp_f32_e32 v86, v58
	v_add_f32_e32 v58, 1.0, v87
	v_pk_mul_f32 v[72:73], v[72:73], v[106:107]
	v_add_co_u32_e32 v106, vcc, s18, v38
	v_rcp_f32_e32 v90, v54
	v_rcp_f32_e32 v87, v53
	v_rcp_f32_e32 v88, v58
	v_add_f32_e32 v53, 1.0, v61
	v_add_f32_e32 v61, 1.0, v105
	v_addc_co_u32_e32 v107, vcc, 0, v39, vcc
	s_movk_i32 s10, 0x6000
	v_add_f32_e32 v56, 1.0, v68
	v_add_f32_e32 v68, 1.0, v69
	v_add_f32_e32 v55, 1.0, v55
	v_add_f32_e32 v63, 1.0, v63
	v_rcp_f32_e32 v67, v66
	v_rcp_f32_e32 v66, v61
	v_add_f32_e32 v61, 1.0, v108
	v_add_co_u32_e32 v108, vcc, s10, v38
	v_add_f32_e32 v69, 1.0, v71
	v_rcp_f32_e32 v54, v55
	v_rcp_f32_e32 v55, v63
	v_rcp_f32_e32 v58, v60
	v_rcp_f32_e32 v63, v20
	v_rcp_f32_e32 v60, v68
	v_add_f32_e32 v20, 1.0, v64
	v_add_f32_e32 v68, 1.0, v109
	v_addc_co_u32_e32 v109, vcc, 0, v39, vcc
	s_mov_b32 s10, 0x9000
	v_rcp_f32_e32 v64, v69
	v_add_f32_e32 v70, 1.0, v70
	v_rcp_f32_e32 v69, v20
	v_add_f32_e32 v20, 1.0, v65
	v_add_f32_e32 v75, 1.0, v110
	v_add_co_u32_e32 v110, vcc, s10, v38
	v_rcp_f32_e32 v71, v70
	v_rcp_f32_e32 v65, v20
	v_rcp_f32_e32 v70, v75
	v_pk_mul_f32 v[82:83], v[82:83], v[90:91]
	v_pk_mul_f32 v[80:81], v[80:81], v[86:87]
	v_pk_mul_f32 v[84:85], v[84:85], v[88:89]
	v_addc_co_u32_e32 v111, vcc, 0, v39, vcc
	v_addc_co_u32_e64 v75, vcc, -1, v39, s[6:7]
	s_nop 0
	v_rcp_f32_e32 v53, v53
	v_rcp_f32_e32 v56, v56
	v_rcp_f32_e32 v57, v57
	v_rcp_f32_e32 v61, v61
	v_rcp_f32_e32 v68, v68
	v_pk_mul_f32 v[42:43], v[42:43], v[52:53]
	v_pk_mul_f32 v[44:45], v[44:45], v[62:63]
	v_pk_mul_f32 v[10:11], v[10:11], v[56:57]
	v_pk_mul_f32 v[6:7], v[6:7], v[66:67]
	v_pk_mul_f32 v[40:41], v[40:41], v[60:61]
	v_pk_mul_f32 v[46:47], v[46:47], v[68:69]
	v_pk_mul_f32 v[12:13], v[12:13], v[64:65]
	v_pk_mul_f32 v[8:9], v[8:9], v[70:71]
	v_pk_mul_f32 v[14:15], v[14:15], v[54:55]
	s_mov_b64 s[6:7], 0x18000
	v_pk_mul_f32 v[16:17], v[16:17], v[58:59]
	v_lshl_add_u64 v[38:39], v[38:39], 0, s[6:7]
	v_pk_fma_f32 v[2:3], v[128:129], v[42:43], v[2:3] op_sel_hi:[0,1,1]
	v_pk_fma_f32 v[4:5], v[128:129], v[44:45], v[4:5] op_sel_hi:[0,1,1]
	v_pk_fma_f32 v[2:3], v[130:131], v[10:11], v[2:3] op_sel_hi:[0,1,1]
	v_pk_fma_f32 v[4:5], v[130:131], v[6:7], v[4:5] op_sel_hi:[0,1,1]
	v_pk_fma_f32 v[2:3], v[132:133], v[40:41], v[2:3] op_sel_hi:[0,1,1]
	v_pk_fma_f32 v[4:5], v[132:133], v[46:47], v[4:5] op_sel_hi:[0,1,1]
	v_pk_fma_f32 v[2:3], v[134:135], v[12:13], v[2:3] op_sel_hi:[0,1,1]
	v_pk_fma_f32 v[4:5], v[134:135], v[8:9], v[4:5] op_sel_hi:[0,1,1]
	v_pk_fma_f32 v[2:3], v[136:137], v[72:73], v[2:3] op_sel_hi:[0,1,1]
	v_pk_fma_f32 v[4:5], v[136:137], v[82:83], v[4:5] op_sel_hi:[0,1,1]
	v_pk_fma_f32 v[2:3], v[138:139], v[50:51], v[2:3] op_sel_hi:[0,1,1]
	v_pk_fma_f32 v[4:5], v[138:139], v[14:15], v[4:5] op_sel_hi:[0,1,1]
	v_pk_fma_f32 v[2:3], v[140:141], v[80:81], v[2:3] op_sel_hi:[0,1,1]
	v_pk_fma_f32 v[4:5], v[140:141], v[84:85], v[4:5] op_sel_hi:[0,1,1]
	v_pk_fma_f32 v[2:3], v[142:143], v[48:49], v[2:3] op_sel_hi:[0,1,1]
	v_pk_fma_f32 v[4:5], v[142:143], v[16:17], v[4:5] op_sel_hi:[0,1,1]
	s_cbranch_scc0 .LBB0_147
	ds_write_b128 v93, v[2:5]
	s_waitcnt lgkmcnt(0)
	s_barrier
	s_and_saveexec_b64 s[6:7], s[34:35]
	s_cbranch_execz .LBB0_150
	s_lshl_b32 s14, s40, 5
	s_and_b64 s[10:11], s[12:13], exec
	s_cselect_b32 s10, 0xc00, 0
	s_add_i32 s10, s14, s10
	v_or_b32_e32 v20, s10, v1
	v_lshl_add_u64 v[2:3], v[20:21], 2, s[0:1]
	global_load_dword v10, v[2:3], off
	ds_read2st64_b32 v[2:3], v96 offset1:2
	ds_read2st64_b32 v[4:5], v96 offset0:4 offset1:6
	ds_read2st64_b32 v[6:7], v96 offset0:8 offset1:10
	ds_read2st64_b32 v[8:9], v96 offset0:12 offset1:14
	s_and_b64 s[10:11], s[12:13], exec
	s_waitcnt lgkmcnt(3)
	v_add_f32_e32 v2, 0, v2
	v_add_f32_e32 v2, v2, v3
	s_waitcnt lgkmcnt(2)
	v_add_f32_e32 v2, v2, v4
	v_add_f32_e32 v2, v2, v5
	s_cselect_b32 s10, 4, 0
	s_waitcnt lgkmcnt(1)
	v_add_f32_e32 v2, v2, v6
	s_movk_i32 s15, 0xc00
	v_mov_b32_e32 v11, s14
	v_or_b32_e32 v3, s10, v19
	v_add_f32_e32 v2, v2, v7
	v_mad_u32_u24 v3, v3, s15, v11
	s_waitcnt lgkmcnt(0)
	v_add_f32_e32 v2, v2, v8
	v_or_b32_e32 v20, v3, v1
	v_add_f32_e32 v2, v2, v9
	s_waitcnt vmcnt(0)
	v_add_f32_e32 v4, v2, v10
	v_lshl_add_u64 v[2:3], v[20:21], 2, s[42:43]
	global_store_dword v[2:3], v4, off
